# nt on the read-once residual loads of the out-proj / down-proj epilogues and on the final output stores, on top of v26
# baseline (speedup 1.0000x reference)
.LBB0_675:
	s_lshr_b32 s0, s94, 3
	s_mulk_i32 s0, 0x6000
	s_ashr_i32 s1, s0, 31
	s_lshl_b64 s[0:1], s[0:1], 2
	s_add_u32 s0, s87, s0
	s_addc_u32 s1, s64, s1
	s_lshl_b32 s18, s94, 8
	v_mov_b32_e32 v199, v183
	v_add_u32_e32 v146, s18, v1
	v_lshl_add_u64 v[130:131], s[0:1], 0, v[198:199]
	v_ashrrev_i32_e32 v147, 31, v146
	v_lshl_add_u64 v[142:143], v[130:131], 0, s[54:55]
	v_add_co_u32_e32 v130, vcc, s65, v130
	v_lshlrev_b64 v[134:135], 14, v[146:147]
	s_nop 0
	v_addc_co_u32_e32 v131, vcc, 0, v131, vcc
	v_lshl_add_u64 v[160:161], v[186:187], 0, v[134:135]
	global_load_dwordx4 v[130:133], v[130:131], off
	s_nop 0
	global_load_dwordx4 v[148:151], v[160:161], off nt
	global_load_dwordx4 v[152:155], v[160:161], off offset:64 nt
	global_load_dwordx4 v[138:141], v[142:143], off offset:64
	global_load_dwordx4 v[134:137], v[142:143], off offset:512
	global_load_dwordx4 v[156:159], v[160:161], off offset:512 nt
	s_nop 0
	global_load_dwordx4 v[142:145], v[142:143], off offset:576
	s_nop 0
	global_load_dwordx4 v[160:163], v[160:161], off offset:576 nt
	v_add_u32_e32 v164, s18, v221
	v_ashrrev_i32_e32 v165, 31, v164
	v_lshlrev_b64 v[164:165], 14, v[164:165]
	v_lshl_add_u64 v[164:165], v[186:187], 0, v[164:165]
	v_readfirstlane_b32 s19, v0
	s_waitcnt vmcnt(0)
	v_pk_fma_f32 v[60:61], v[60:61], v[140:141], v[154:155]
	v_pk_fma_f32 v[58:59], v[58:59], v[138:139], v[152:153]
	v_pk_fma_f32 v[28:29], v[28:29], v[136:137], v[158:159]
	v_pk_fma_f32 v[92:93], v[92:93], v[132:133], v[150:151]
	v_pk_fma_f32 v[90:91], v[90:91], v[130:131], v[148:149]
	v_pk_fma_f32 v[26:27], v[26:27], v[134:135], v[156:157]
	v_pk_fma_f32 v[4:5], v[4:5], v[144:145], v[162:163]
	v_pk_fma_f32 v[2:3], v[2:3], v[142:143], v[160:161]
	s_nop 0
	global_load_dwordx4 v[148:151], v[164:165], off nt
	global_load_dwordx4 v[152:155], v[164:165], off offset:64 nt
	global_load_dwordx4 v[156:159], v[164:165], off offset:512 nt
	global_load_dwordx4 v[160:163], v[164:165], off offset:576 nt
	v_add_u32_e32 v164, s18, v223
	v_ashrrev_i32_e32 v165, 31, v164
	v_lshlrev_b64 v[164:165], 14, v[164:165]
	v_lshl_add_u64 v[164:165], v[186:187], 0, v[164:165]
	v_mul_f32_e32 v166, v59, v59
	v_mul_f32_e32 v167, v61, v61
	v_mul_f32_e32 v168, v27, v27
	v_mul_f32_e32 v169, v29, v29
	v_fmac_f32_e32 v166, v58, v58
	v_fmac_f32_e32 v167, v60, v60
	v_mul_f32_e32 v170, v3, v3
	v_mul_f32_e32 v171, v5, v5
	v_fmac_f32_e32 v168, v26, v26
	v_fmac_f32_e32 v169, v28, v28
	v_fmac_f32_e32 v170, v2, v2
	v_fmac_f32_e32 v171, v4, v4
	s_waitcnt vmcnt(3)
	v_pk_fma_f32 v[100:101], v[100:101], v[132:133], v[150:151]
	v_pk_fma_f32 v[98:99], v[98:99], v[130:131], v[148:149]
	s_waitcnt vmcnt(2)
	v_pk_fma_f32 v[68:69], v[68:69], v[140:141], v[154:155]
	v_pk_fma_f32 v[66:67], v[66:67], v[138:139], v[152:153]
	s_waitcnt vmcnt(1)
	v_pk_fma_f32 v[36:37], v[36:37], v[136:137], v[158:159]
	v_pk_fma_f32 v[34:35], v[34:35], v[134:135], v[156:157]
	s_waitcnt vmcnt(0)
	v_pk_fma_f32 v[8:9], v[8:9], v[144:145], v[162:163]
	v_pk_fma_f32 v[6:7], v[6:7], v[142:143], v[160:161]
	s_nop 0
	global_load_dwordx4 v[148:151], v[164:165], off nt
	global_load_dwordx4 v[152:155], v[164:165], off offset:64 nt
	global_load_dwordx4 v[156:159], v[164:165], off offset:512 nt
	global_load_dwordx4 v[160:163], v[164:165], off offset:576 nt
	v_add_u32_e32 v164, s18, v224
	v_ashrrev_i32_e32 v165, 31, v164
	v_lshlrev_b64 v[164:165], 14, v[164:165]
	v_lshl_add_u64 v[164:165], v[186:187], 0, v[164:165]
	s_waitcnt vmcnt(3)
	v_pk_fma_f32 v[104:105], v[104:105], v[132:133], v[150:151]
	v_pk_fma_f32 v[102:103], v[102:103], v[130:131], v[148:149]
	s_waitcnt vmcnt(2)
	v_pk_fma_f32 v[72:73], v[72:73], v[140:141], v[154:155]
	v_pk_fma_f32 v[70:71], v[70:71], v[138:139], v[152:153]
	s_waitcnt vmcnt(1)
	v_pk_fma_f32 v[40:41], v[40:41], v[136:137], v[158:159]
	v_pk_fma_f32 v[38:39], v[38:39], v[134:135], v[156:157]
	s_waitcnt vmcnt(0)
	v_pk_fma_f32 v[12:13], v[12:13], v[144:145], v[162:163]
	v_pk_fma_f32 v[10:11], v[10:11], v[142:143], v[160:161]
	s_nop 0
	global_load_dwordx4 v[148:151], v[164:165], off nt
	global_load_dwordx4 v[152:155], v[164:165], off offset:64 nt
	global_load_dwordx4 v[156:159], v[164:165], off offset:512 nt
	global_load_dwordx4 v[160:163], v[164:165], off offset:576 nt
	v_add_u32_e32 v164, s18, v225
	v_ashrrev_i32_e32 v165, 31, v164
	v_lshlrev_b64 v[164:165], 14, v[164:165]
	v_lshl_add_u64 v[164:165], v[186:187], 0, v[164:165]
	s_waitcnt vmcnt(3)
	v_pk_fma_f32 v[112:113], v[112:113], v[132:133], v[150:151]
	v_pk_fma_f32 v[110:111], v[110:111], v[130:131], v[148:149]
	s_waitcnt vmcnt(2)
	v_pk_fma_f32 v[80:81], v[80:81], v[140:141], v[154:155]
	v_pk_fma_f32 v[78:79], v[78:79], v[138:139], v[152:153]
	s_waitcnt vmcnt(1)
	v_pk_fma_f32 v[48:49], v[48:49], v[136:137], v[158:159]
	v_pk_fma_f32 v[46:47], v[46:47], v[134:135], v[156:157]
	s_waitcnt vmcnt(0)
	v_pk_fma_f32 v[16:17], v[16:17], v[144:145], v[162:163]
	v_pk_fma_f32 v[14:15], v[14:15], v[142:143], v[160:161]
	s_nop 0
	global_load_dwordx4 v[148:151], v[164:165], off nt
	global_load_dwordx4 v[152:155], v[164:165], off offset:64 nt
	global_load_dwordx4 v[156:159], v[164:165], off offset:512 nt
	global_load_dwordx4 v[160:163], v[164:165], off offset:576 nt
	v_add_u32_e32 v164, 0x90, v146
	v_ashrrev_i32_e32 v165, 31, v164
	v_lshlrev_b64 v[164:165], 14, v[164:165]
	v_lshl_add_u64 v[164:165], v[186:187], 0, v[164:165]
	s_waitcnt vmcnt(3)
	v_pk_fma_f32 v[116:117], v[116:117], v[132:133], v[150:151]
	v_pk_fma_f32 v[114:115], v[114:115], v[130:131], v[148:149]
	s_waitcnt vmcnt(2)
	v_pk_fma_f32 v[84:85], v[84:85], v[140:141], v[154:155]
	v_pk_fma_f32 v[82:83], v[82:83], v[138:139], v[152:153]
	s_waitcnt vmcnt(1)
	v_pk_fma_f32 v[52:53], v[52:53], v[136:137], v[158:159]
	v_pk_fma_f32 v[50:51], v[50:51], v[134:135], v[156:157]
	s_waitcnt vmcnt(0)
	v_pk_fma_f32 v[20:21], v[20:21], v[144:145], v[162:163]
	v_pk_fma_f32 v[18:19], v[18:19], v[142:143], v[160:161]
	s_nop 0
	global_load_dwordx4 v[148:151], v[164:165], off nt
	global_load_dwordx4 v[152:155], v[164:165], off offset:64 nt
	global_load_dwordx4 v[156:159], v[164:165], off offset:512 nt
	global_load_dwordx4 v[160:163], v[164:165], off offset:576 nt
	v_add_u32_e32 v164, 0xa0, v146
	v_ashrrev_i32_e32 v165, 31, v164
	v_lshlrev_b64 v[164:165], 14, v[164:165]
	v_lshl_add_u64 v[164:165], v[186:187], 0, v[164:165]
	v_add_u32_e32 v146, 0xb0, v146
	v_ashrrev_i32_e32 v147, 31, v146
	v_lshlrev_b64 v[146:147], 14, v[146:147]
	v_lshl_add_u64 v[146:147], v[186:187], 0, v[146:147]
	s_waitcnt vmcnt(3)
	v_pk_fma_f32 v[120:121], v[120:121], v[132:133], v[150:151]
	v_pk_fma_f32 v[118:119], v[118:119], v[130:131], v[148:149]
	s_waitcnt vmcnt(2)
	v_pk_fma_f32 v[88:89], v[88:89], v[140:141], v[154:155]
	v_pk_fma_f32 v[86:87], v[86:87], v[138:139], v[152:153]
	s_waitcnt vmcnt(1)
	v_pk_fma_f32 v[56:57], v[56:57], v[136:137], v[158:159]
	v_pk_fma_f32 v[54:55], v[54:55], v[134:135], v[156:157]
	s_waitcnt vmcnt(0)
	v_pk_fma_f32 v[24:25], v[24:25], v[144:145], v[162:163]
	v_pk_fma_f32 v[22:23], v[22:23], v[142:143], v[160:161]
	s_nop 0
	global_load_dwordx4 v[148:151], v[164:165], off nt
	global_load_dwordx4 v[152:155], v[164:165], off offset:64 nt
	global_load_dwordx4 v[156:159], v[164:165], off offset:512 nt
	global_load_dwordx4 v[160:163], v[164:165], off offset:576 nt
	s_waitcnt vmcnt(3)
	v_pk_fma_f32 v[124:125], v[124:125], v[132:133], v[150:151]
	v_pk_fma_f32 v[122:123], v[122:123], v[130:131], v[148:149]
	s_waitcnt vmcnt(2)
	v_pk_fma_f32 v[96:97], v[96:97], v[140:141], v[154:155]
	v_pk_fma_f32 v[94:95], v[94:95], v[138:139], v[152:153]
	s_waitcnt vmcnt(1)
	v_pk_fma_f32 v[64:65], v[64:65], v[136:137], v[158:159]
	v_pk_fma_f32 v[62:63], v[62:63], v[134:135], v[156:157]
	s_waitcnt vmcnt(0)
	v_pk_fma_f32 v[32:33], v[32:33], v[144:145], v[162:163]
	v_pk_fma_f32 v[30:31], v[30:31], v[142:143], v[160:161]
	v_mul_f32_e32 v148, v91, v91
	global_load_dwordx4 v[150:153], v[146:147], off nt
	global_load_dwordx4 v[154:157], v[146:147], off offset:64 nt
	global_load_dwordx4 v[158:161], v[146:147], off offset:512 nt
	global_load_dwordx4 v[162:165], v[146:147], off offset:576 nt
	v_mul_f32_e32 v149, v93, v93
	v_and_b32_e32 v147, 64, v234
	v_fmac_f32_e32 v148, v90, v90
	v_fmac_f32_e32 v149, v92, v92
	v_xor_b32_e32 v146, 16, v234
	v_add_u32_e32 v147, 64, v147
	v_add_f32_e32 v148, v148, v149
	v_add_f32_e32 v149, v166, v167
	v_cmp_lt_i32_e32 vcc, v146, v147
	v_add_f32_e32 v166, v168, v169
	v_add_f32_e32 v148, v148, v149
	v_cndmask_b32_e32 v146, v234, v146, vcc
	v_add_f32_e32 v167, v170, v171
	v_add_f32_e32 v148, v166, v148
	v_lshlrev_b32_e32 v146, 2, v146
	v_add_f32_e32 v148, v167, v148
	ds_bpermute_b32 v149, v146, v148
	v_xor_b32_e32 v166, 32, v234
	v_cmp_lt_i32_e32 vcc, v166, v147
	s_waitcnt vmcnt(3)
	v_pk_fma_f32 v[128:129], v[128:129], v[132:133], v[152:153]
	v_cndmask_b32_e32 v147, v234, v166, vcc
	v_lshlrev_b32_e32 v199, 2, v147
	s_waitcnt lgkmcnt(0)
	v_add_f32_e32 v147, v148, v149
	ds_bpermute_b32 v148, v199, v147
	v_pk_fma_f32 v[126:127], v[126:127], v[130:131], v[150:151]
	s_waitcnt vmcnt(2)
	v_pk_fma_f32 v[108:109], v[108:109], v[140:141], v[156:157]
	v_pk_fma_f32 v[106:107], v[106:107], v[138:139], v[154:155]
	s_waitcnt vmcnt(1)
	v_pk_fma_f32 v[76:77], v[76:77], v[136:137], v[160:161]
	v_pk_fma_f32 v[74:75], v[74:75], v[134:135], v[158:159]
	s_waitcnt vmcnt(0)
	v_pk_fma_f32 v[44:45], v[44:45], v[144:145], v[164:165]
	v_pk_fma_f32 v[42:43], v[42:43], v[142:143], v[162:163]
	s_nop 0
	s_and_saveexec_b64 s[16:17], s[4:5]
	s_cbranch_execz .LBB0_677
	s_waitcnt lgkmcnt(0)
	v_add_f32_e32 v130, v147, v148
	v_add_u32_e32 v131, s80, v226
	ds_write_b32 v131, v130

.LBB0_1043:
	s_lshl_b32 s62, s61, 8
	v_add_u32_e32 v172, s62, v1
	v_or_b32_e32 v130, v172, v183
	v_ashrrev_i32_e32 v131, 31, v130
	v_lshlrev_b64 v[130:131], 13, v[130:131]
	v_lshl_add_u64 v[130:131], v[160:161], 0, v[130:131]
	s_lshr_b32 s8, s61, 3
	global_load_dwordx4 v[142:145], v[130:131], off nt
	global_load_dwordx4 v[174:177], v[130:131], off offset:32 nt
	global_load_dwordx4 v[178:181], v[130:131], off offset:256 nt
	global_load_dwordx4 v[210:213], v[130:131], off offset:288 nt
	s_mulk_i32 s8, 0x6000
	s_ashr_i32 s9, s8, 31
	v_lshl_add_u64 v[130:131], s[8:9], 2, v[158:159]
	global_load_dwordx4 v[134:137], v[130:131], off
	global_load_dwordx4 v[146:149], v[130:131], off offset:64
	global_load_dwordx4 v[138:141], v[130:131], off offset:512
	s_nop 0
	global_load_dwordx4 v[130:133], v[130:131], off offset:576
	v_readfirstlane_b32 s10, v0
	s_waitcnt vmcnt(0)
	v_mov_b32_e32 v154, v144
	v_mov_b32_e32 v173, v145
	s_nop 0
	v_permlane16_swap_b32_e32 v142, v154
	v_permlane16_swap_b32_e32 v143, v173
	v_mov_b32_e32 v214, v176
	v_mov_b32_e32 v215, v177
	v_mov_b32_e32 v219, v180
	v_mov_b32_e32 v221, v181
	v_mov_b32_e32 v227, v212
	v_mov_b32_e32 v229, v213
	v_lshlrev_b32_e32 v144, 16, v142
	v_and_b32_e32 v145, 0xffff0000, v142
	v_lshlrev_b32_e32 v142, 16, v143
	v_and_b32_e32 v143, 0xffff0000, v143
	v_permlane16_swap_b32_e32 v174, v214
	v_permlane16_swap_b32_e32 v175, v215
	v_permlane16_swap_b32_e32 v178, v219
	v_permlane16_swap_b32_e32 v179, v221
	v_permlane16_swap_b32_e32 v210, v227
	v_permlane16_swap_b32_e32 v211, v229
	v_pk_fma_f32 v[92:93], v[92:93], v[136:137], v[142:143]
	v_or_b32_e32 v142, v172, v184
	v_lshlrev_b32_e32 v176, 16, v154
	v_and_b32_e32 v177, 0xffff0000, v154
	v_lshlrev_b32_e32 v180, 16, v173
	v_and_b32_e32 v181, 0xffff0000, v173
	v_lshlrev_b32_e32 v188, 16, v174
	v_and_b32_e32 v189, 0xffff0000, v174
	v_lshlrev_b32_e32 v174, 16, v175
	v_and_b32_e32 v175, 0xffff0000, v175
	v_lshlrev_b32_e32 v212, 16, v214
	v_and_b32_e32 v213, 0xffff0000, v214
	v_lshlrev_b32_e32 v214, 16, v215
	v_and_b32_e32 v215, 0xffff0000, v215
	v_lshlrev_b32_e32 v216, 16, v178
	v_and_b32_e32 v217, 0xffff0000, v178
	v_lshlrev_b32_e32 v178, 16, v179
	v_and_b32_e32 v179, 0xffff0000, v179
	v_lshlrev_b32_e32 v218, 16, v219
	v_and_b32_e32 v219, 0xffff0000, v219
	v_lshlrev_b32_e32 v220, 16, v221
	v_and_b32_e32 v221, 0xffff0000, v221
	v_lshlrev_b32_e32 v224, 16, v210
	v_and_b32_e32 v225, 0xffff0000, v210
	v_lshlrev_b32_e32 v210, 16, v211
	v_and_b32_e32 v211, 0xffff0000, v211
	v_lshlrev_b32_e32 v226, 16, v227
	v_and_b32_e32 v227, 0xffff0000, v227
	v_lshlrev_b32_e32 v228, 16, v229
	v_and_b32_e32 v229, 0xffff0000, v229
	v_ashrrev_i32_e32 v143, 31, v142
	v_pk_fma_f32 v[90:91], v[90:91], v[134:135], v[144:145]
	v_pk_fma_f32 v[48:49], v[48:49], v[136:137], v[180:181]
	v_pk_fma_f32 v[46:47], v[46:47], v[134:135], v[176:177]
	v_pk_fma_f32 v[76:77], v[76:77], v[148:149], v[174:175]
	v_pk_fma_f32 v[74:75], v[74:75], v[146:147], v[188:189]
	v_pk_fma_f32 v[44:45], v[44:45], v[148:149], v[214:215]
	v_pk_fma_f32 v[42:43], v[42:43], v[146:147], v[212:213]
	v_pk_fma_f32 v[72:73], v[72:73], v[140:141], v[178:179]
	v_pk_fma_f32 v[70:71], v[70:71], v[138:139], v[216:217]
	v_pk_fma_f32 v[36:37], v[36:37], v[140:141], v[220:221]
	v_pk_fma_f32 v[34:35], v[34:35], v[138:139], v[218:219]
	v_pk_fma_f32 v[68:69], v[68:69], v[132:133], v[210:211]
	v_pk_fma_f32 v[66:67], v[66:67], v[130:131], v[224:225]
	v_pk_fma_f32 v[40:41], v[40:41], v[132:133], v[228:229]
	v_pk_fma_f32 v[38:39], v[38:39], v[130:131], v[226:227]
	v_lshlrev_b64 v[142:143], 13, v[142:143]
	v_lshl_add_u64 v[174:175], v[160:161], 0, v[142:143]
	global_load_dwordx4 v[142:145], v[174:175], off nt
	global_load_dwordx4 v[176:179], v[174:175], off offset:32 nt
	global_load_dwordx4 v[210:213], v[174:175], off offset:256 nt
	global_load_dwordx4 v[214:217], v[174:175], off offset:288 nt
	v_add_u32_e32 v174, s62, v185
	v_or_b32_e32 v180, v174, v183
	s_waitcnt vmcnt(3)
	v_mov_b32_e32 v154, v144
	v_mov_b32_e32 v173, v145
	s_waitcnt vmcnt(2)
	v_mov_b32_e32 v175, v178
	v_mov_b32_e32 v181, v179
	s_waitcnt vmcnt(1)
	v_mov_b32_e32 v225, v212
	v_mov_b32_e32 v227, v213
	s_waitcnt vmcnt(0)
	v_mov_b32_e32 v231, v216
	v_mov_b32_e32 v233, v217
	v_permlane16_swap_b32_e32 v142, v154
	v_permlane16_swap_b32_e32 v143, v173
	v_permlane16_swap_b32_e32 v176, v175
	v_permlane16_swap_b32_e32 v177, v181
	v_permlane16_swap_b32_e32 v210, v225
	v_permlane16_swap_b32_e32 v211, v227
	v_permlane16_swap_b32_e32 v214, v231
	v_permlane16_swap_b32_e32 v215, v233
	v_lshlrev_b32_e32 v144, 16, v142
	v_and_b32_e32 v145, 0xffff0000, v142
	v_lshlrev_b32_e32 v142, 16, v143
	v_and_b32_e32 v143, 0xffff0000, v143
	v_lshlrev_b32_e32 v178, 16, v154
	v_and_b32_e32 v179, 0xffff0000, v154
	v_lshlrev_b32_e32 v188, 16, v173
	v_and_b32_e32 v189, 0xffff0000, v173
	v_lshlrev_b32_e32 v212, 16, v176
	v_and_b32_e32 v213, 0xffff0000, v176
	v_lshlrev_b32_e32 v176, 16, v177
	v_and_b32_e32 v177, 0xffff0000, v177
	v_lshlrev_b32_e32 v216, 16, v175
	v_and_b32_e32 v217, 0xffff0000, v175
	v_lshlrev_b32_e32 v218, 16, v181
	v_and_b32_e32 v219, 0xffff0000, v181
	v_lshlrev_b32_e32 v220, 16, v210
	v_and_b32_e32 v221, 0xffff0000, v210
	v_lshlrev_b32_e32 v210, 16, v211
	v_and_b32_e32 v211, 0xffff0000, v211
	v_lshlrev_b32_e32 v224, 16, v225
	v_and_b32_e32 v225, 0xffff0000, v225
	v_lshlrev_b32_e32 v226, 16, v227
	v_and_b32_e32 v227, 0xffff0000, v227
	v_lshlrev_b32_e32 v228, 16, v214
	v_and_b32_e32 v229, 0xffff0000, v214
	v_lshlrev_b32_e32 v214, 16, v215
	v_and_b32_e32 v215, 0xffff0000, v215
	v_lshlrev_b32_e32 v230, 16, v231
	v_and_b32_e32 v231, 0xffff0000, v231
	v_lshlrev_b32_e32 v232, 16, v233
	v_and_b32_e32 v233, 0xffff0000, v233
	v_ashrrev_i32_e32 v181, 31, v180
	v_pk_fma_f32 v[128:129], v[128:129], v[136:137], v[142:143]
	v_pk_fma_f32 v[126:127], v[126:127], v[134:135], v[144:145]
	v_pk_fma_f32 v[112:113], v[112:113], v[136:137], v[188:189]
	v_pk_fma_f32 v[110:111], v[110:111], v[134:135], v[178:179]
	v_pk_fma_f32 v[124:125], v[124:125], v[148:149], v[176:177]
	v_pk_fma_f32 v[122:123], v[122:123], v[146:147], v[212:213]
	v_pk_fma_f32 v[108:109], v[108:109], v[148:149], v[218:219]
	v_pk_fma_f32 v[106:107], v[106:107], v[146:147], v[216:217]
	v_pk_fma_f32 v[120:121], v[120:121], v[140:141], v[210:211]
	v_pk_fma_f32 v[118:119], v[118:119], v[138:139], v[220:221]
	v_pk_fma_f32 v[104:105], v[104:105], v[140:141], v[226:227]
	v_pk_fma_f32 v[102:103], v[102:103], v[138:139], v[224:225]
	v_pk_fma_f32 v[116:117], v[116:117], v[132:133], v[214:215]
	v_pk_fma_f32 v[114:115], v[114:115], v[130:131], v[228:229]
	v_pk_fma_f32 v[100:101], v[100:101], v[132:133], v[232:233]
	v_pk_fma_f32 v[98:99], v[98:99], v[130:131], v[230:231]
	v_lshlrev_b64 v[142:143], 13, v[180:181]
	v_lshl_add_u64 v[180:181], v[160:161], 0, v[142:143]
	global_load_dwordx4 v[142:145], v[180:181], off nt
	global_load_dwordx4 v[176:179], v[180:181], off offset:32 nt
	global_load_dwordx4 v[210:213], v[180:181], off offset:256 nt
	global_load_dwordx4 v[214:217], v[180:181], off offset:288 nt
	v_or_b32_e32 v180, v174, v184
	v_ashrrev_i32_e32 v181, 31, v180
	v_lshlrev_b64 v[180:181], 13, v[180:181]
	v_lshl_add_u64 v[180:181], v[160:161], 0, v[180:181]
	s_waitcnt vmcnt(3)
	v_mov_b32_e32 v154, v144
	v_mov_b32_e32 v173, v145
	s_waitcnt vmcnt(2)
	v_mov_b32_e32 v175, v178
	v_mov_b32_e32 v219, v179
	s_waitcnt vmcnt(1)
	v_mov_b32_e32 v225, v212
	v_mov_b32_e32 v227, v213
	s_waitcnt vmcnt(0)
	v_mov_b32_e32 v231, v216
	v_mov_b32_e32 v233, v217
	v_permlane16_swap_b32_e32 v142, v154
	v_permlane16_swap_b32_e32 v143, v173
	v_permlane16_swap_b32_e32 v176, v175
	v_permlane16_swap_b32_e32 v177, v219
	v_permlane16_swap_b32_e32 v210, v225
	v_permlane16_swap_b32_e32 v211, v227
	v_permlane16_swap_b32_e32 v214, v231
	v_permlane16_swap_b32_e32 v215, v233
	v_lshlrev_b32_e32 v144, 16, v142
	v_and_b32_e32 v145, 0xffff0000, v142
	v_lshlrev_b32_e32 v142, 16, v143
	v_and_b32_e32 v143, 0xffff0000, v143
	v_lshlrev_b32_e32 v178, 16, v154
	v_and_b32_e32 v179, 0xffff0000, v154
	v_lshlrev_b32_e32 v188, 16, v173
	v_and_b32_e32 v189, 0xffff0000, v173
	v_lshlrev_b32_e32 v212, 16, v176
	v_and_b32_e32 v213, 0xffff0000, v176
	v_lshlrev_b32_e32 v176, 16, v177
	v_and_b32_e32 v177, 0xffff0000, v177
	v_lshlrev_b32_e32 v216, 16, v175
	v_and_b32_e32 v217, 0xffff0000, v175
	v_lshlrev_b32_e32 v218, 16, v219
	v_and_b32_e32 v219, 0xffff0000, v219
	v_lshlrev_b32_e32 v220, 16, v210
	v_and_b32_e32 v221, 0xffff0000, v210
	v_lshlrev_b32_e32 v210, 16, v211
	v_and_b32_e32 v211, 0xffff0000, v211
	v_lshlrev_b32_e32 v224, 16, v225
	v_and_b32_e32 v225, 0xffff0000, v225
	v_lshlrev_b32_e32 v226, 16, v227
	v_and_b32_e32 v227, 0xffff0000, v227
	v_lshlrev_b32_e32 v228, 16, v214
	v_and_b32_e32 v229, 0xffff0000, v214
	v_lshlrev_b32_e32 v214, 16, v215
	v_and_b32_e32 v215, 0xffff0000, v215
	v_lshlrev_b32_e32 v230, 16, v231
	v_and_b32_e32 v231, 0xffff0000, v231
	v_lshlrev_b32_e32 v232, 16, v233
	v_and_b32_e32 v233, 0xffff0000, v233
	v_pk_fma_f32 v[96:97], v[96:97], v[136:137], v[142:143]
	v_pk_fma_f32 v[94:95], v[94:95], v[134:135], v[144:145]
	v_pk_fma_f32 v[84:85], v[84:85], v[136:137], v[188:189]
	v_pk_fma_f32 v[82:83], v[82:83], v[134:135], v[178:179]
	v_pk_fma_f32 v[88:89], v[88:89], v[148:149], v[176:177]
	v_pk_fma_f32 v[86:87], v[86:87], v[146:147], v[212:213]
	v_pk_fma_f32 v[80:81], v[80:81], v[148:149], v[218:219]
	v_pk_fma_f32 v[78:79], v[78:79], v[146:147], v[216:217]
	v_pk_fma_f32 v[64:65], v[64:65], v[140:141], v[210:211]
	v_pk_fma_f32 v[62:63], v[62:63], v[138:139], v[220:221]
	v_pk_fma_f32 v[56:57], v[56:57], v[140:141], v[226:227]
	v_pk_fma_f32 v[54:55], v[54:55], v[138:139], v[224:225]
	v_pk_fma_f32 v[60:61], v[60:61], v[132:133], v[214:215]
	v_pk_fma_f32 v[58:59], v[58:59], v[130:131], v[228:229]
	v_pk_fma_f32 v[52:53], v[52:53], v[132:133], v[232:233]
	v_pk_fma_f32 v[50:51], v[50:51], v[130:131], v[230:231]
	s_nop 0
	global_load_dwordx4 v[142:145], v[180:181], off nt
	global_load_dwordx4 v[176:179], v[180:181], off offset:32 nt
	global_load_dwordx4 v[210:213], v[180:181], off offset:256 nt
	global_load_dwordx4 v[214:217], v[180:181], off offset:288 nt
	s_waitcnt vmcnt(3)
	v_permlane16_swap_b32_e32 v142, v144
	s_waitcnt vmcnt(2)
	v_mov_b32_e32 v154, v178
	v_mov_b32_e32 v173, v179
	s_waitcnt vmcnt(1)
	v_mov_b32_e32 v175, v212
	v_mov_b32_e32 v227, v213
	s_waitcnt vmcnt(0)
	v_mov_b32_e32 v231, v216
	v_mov_b32_e32 v233, v217
	v_permlane16_swap_b32_e32 v143, v145
	v_permlane16_swap_b32_e32 v176, v154
	v_permlane16_swap_b32_e32 v177, v173
	v_permlane16_swap_b32_e32 v210, v175
	v_permlane16_swap_b32_e32 v211, v227
	v_permlane16_swap_b32_e32 v214, v231
	v_permlane16_swap_b32_e32 v215, v233
	v_lshlrev_b32_e32 v178, 16, v142
	v_and_b32_e32 v179, 0xffff0000, v142
	v_lshlrev_b32_e32 v142, 16, v143
	v_and_b32_e32 v143, 0xffff0000, v143
	v_lshlrev_b32_e32 v180, 16, v144
	v_and_b32_e32 v181, 0xffff0000, v144
	v_lshlrev_b32_e32 v188, 16, v145
	v_and_b32_e32 v189, 0xffff0000, v145
	v_lshlrev_b32_e32 v212, 16, v176
	v_and_b32_e32 v213, 0xffff0000, v176
	v_lshlrev_b32_e32 v176, 16, v177
	v_and_b32_e32 v177, 0xffff0000, v177
	v_lshlrev_b32_e32 v216, 16, v154
	v_and_b32_e32 v217, 0xffff0000, v154
	v_lshlrev_b32_e32 v218, 16, v173
	v_and_b32_e32 v219, 0xffff0000, v173
	v_lshlrev_b32_e32 v220, 16, v210
	v_and_b32_e32 v221, 0xffff0000, v210
	v_lshlrev_b32_e32 v210, 16, v211
	v_and_b32_e32 v211, 0xffff0000, v211
	v_lshlrev_b32_e32 v224, 16, v175
	v_and_b32_e32 v225, 0xffff0000, v175
	v_lshlrev_b32_e32 v226, 16, v227
	v_and_b32_e32 v227, 0xffff0000, v227
	v_lshlrev_b32_e32 v228, 16, v214
	v_and_b32_e32 v229, 0xffff0000, v214
	v_lshlrev_b32_e32 v214, 16, v215
	v_and_b32_e32 v215, 0xffff0000, v215
	v_lshlrev_b32_e32 v230, 16, v231
	v_and_b32_e32 v231, 0xffff0000, v231
	v_lshlrev_b32_e32 v232, 16, v233
	v_and_b32_e32 v233, 0xffff0000, v233
	v_pk_fma_f32 v[144:145], v[32:33], v[136:137], v[142:143]
	v_pk_fma_f32 v[142:143], v[30:31], v[134:135], v[178:179]
	v_pk_fma_f32 v[24:25], v[24:25], v[136:137], v[188:189]
	v_pk_fma_f32 v[22:23], v[22:23], v[134:135], v[180:181]
	v_pk_fma_f32 v[136:137], v[28:29], v[148:149], v[176:177]
	v_pk_fma_f32 v[134:135], v[26:27], v[146:147], v[212:213]
	v_pk_fma_f32 v[20:21], v[20:21], v[148:149], v[218:219]
	v_pk_fma_f32 v[18:19], v[18:19], v[146:147], v[216:217]
	v_pk_fma_f32 v[32:33], v[16:17], v[140:141], v[210:211]
	v_pk_fma_f32 v[30:31], v[14:15], v[138:139], v[220:221]
	v_pk_fma_f32 v[12:13], v[12:13], v[140:141], v[226:227]
	v_pk_fma_f32 v[10:11], v[10:11], v[138:139], v[224:225]
	v_pk_fma_f32 v[28:29], v[8:9], v[132:133], v[214:215]
	v_pk_fma_f32 v[26:27], v[6:7], v[130:131], v[228:229]
	v_pk_fma_f32 v[4:5], v[4:5], v[132:133], v[232:233]
	v_pk_fma_f32 v[2:3], v[2:3], v[130:131], v[230:231]
	v_mul_f32_e32 v148, v91, v91
	global_load_dwordx4 v[138:141], v[162:163], off
	global_load_dwordx4 v[130:133], v[162:163], off offset:64
	global_load_dwordx4 v[14:17], v[162:163], off offset:512
	global_load_dwordx4 v[6:9], v[162:163], off offset:576
	v_mul_f32_e32 v149, v93, v93
	v_fmac_f32_e32 v148, v90, v90
	v_fmac_f32_e32 v149, v92, v92
	v_add_f32_e32 v148, v148, v149
	v_mul_f32_e32 v149, v75, v75
	v_mul_f32_e32 v154, v77, v77
	v_fmac_f32_e32 v149, v74, v74
	v_fmac_f32_e32 v154, v76, v76
	v_add_f32_e32 v149, v149, v154
	v_add_f32_e32 v148, v148, v149
	v_mul_f32_e32 v149, v71, v71
	v_mul_f32_e32 v154, v73, v73
	v_fmac_f32_e32 v149, v70, v70
	v_fmac_f32_e32 v154, v72, v72
	v_and_b32_e32 v147, 64, v203
	v_add_f32_e32 v149, v149, v154
	v_xor_b32_e32 v146, 16, v203
	v_add_u32_e32 v147, 64, v147
	v_add_f32_e32 v148, v149, v148
	v_mul_f32_e32 v149, v67, v67
	v_mul_f32_e32 v154, v69, v69
	v_cmp_lt_i32_e32 vcc, v146, v147
	v_fmac_f32_e32 v149, v66, v66
	v_fmac_f32_e32 v154, v68, v68
	v_cndmask_b32_e32 v146, v203, v146, vcc
	v_add_f32_e32 v149, v149, v154
	v_lshlrev_b32_e32 v146, 2, v146
	v_add_f32_e32 v148, v149, v148
	ds_bpermute_b32 v149, v146, v148
	v_xor_b32_e32 v154, 32, v203
	v_cmp_lt_i32_e32 vcc, v154, v147
	s_nop 1
	v_cndmask_b32_e32 v147, v203, v154, vcc
	v_lshlrev_b32_e32 v173, 2, v147
	s_waitcnt lgkmcnt(0)
	v_add_f32_e32 v147, v148, v149
	ds_bpermute_b32 v148, v173, v147
	s_and_saveexec_b64 s[8:9], s[0:1]
	s_cbranch_execz .LBB0_1045
	s_waitcnt lgkmcnt(0)
	v_add_f32_e32 v147, v147, v148
	v_add_u32_e32 v148, s54, v186
	ds_write_b32 v148, v147

.LBB0_1083:
	s_or_b64 exec, exec, s[10:11]
	s_and_b64 s[10:11], s[6:7], s[44:45]
	s_and_saveexec_b64 s[8:9], s[10:11]
	v_mov_b32_e32 v146, s59
	ds_write_b32 v146, v204
	s_or_b64 exec, exec, s[8:9]
	s_waitcnt vmcnt(0) lgkmcnt(0)
	s_barrier
	s_waitcnt lgkmcnt(0)
	v_mov_b32_e32 v147, s59
	ds_read_b32 v146, v194
	ds_read_b32 v147, v147
	v_ashrrev_i32_e32 v173, 31, v172
	v_lshlrev_b64 v[148:149], 14, v[172:173]
	v_lshl_add_u64 v[148:149], v[164:165], 0, v[148:149]
	v_ashrrev_i32_e32 v175, 31, v174
	s_waitcnt lgkmcnt(0)
	v_pk_mul_f32 v[92:93], v[92:93], v[146:147] op_sel_hi:[1,0]
	v_pk_mul_f32 v[90:91], v[90:91], v[146:147] op_sel_hi:[1,0]
	v_pk_mul_f32 v[76:77], v[76:77], v[146:147] op_sel_hi:[1,0]
	v_pk_mul_f32 v[74:75], v[74:75], v[146:147] op_sel_hi:[1,0]
	v_pk_mul_f32 v[72:73], v[72:73], v[146:147] op_sel_hi:[1,0]
	v_pk_mul_f32 v[70:71], v[70:71], v[146:147] op_sel_hi:[1,0]
	v_pk_mul_f32 v[68:69], v[68:69], v[146:147] op_sel_hi:[1,0]
	v_pk_mul_f32 v[66:67], v[66:67], v[146:147] op_sel_hi:[1,0]
	v_pk_mul_f32 v[92:93], v[140:141], v[92:93]
	v_pk_mul_f32 v[90:91], v[138:139], v[90:91]
	v_cmp_eq_u32_e32 vcc, 0, v147
	v_pk_mul_f32 v[76:77], v[132:133], v[76:77]
	v_pk_mul_f32 v[74:75], v[130:131], v[74:75]
	v_pk_mul_f32 v[72:73], v[16:17], v[72:73]
	v_pk_mul_f32 v[70:71], v[14:15], v[70:71]
	v_pk_mul_f32 v[68:69], v[8:9], v[68:69]
	v_pk_mul_f32 v[66:67], v[6:7], v[66:67]
	v_cndmask_b32_e32 v93, v209, v93, vcc
	v_cndmask_b32_e32 v92, v209, v92, vcc
	v_cndmask_b32_e32 v91, v209, v91, vcc
	v_cndmask_b32_e32 v90, v209, v90, vcc
	v_cndmask_b32_e32 v77, v209, v77, vcc
	v_cndmask_b32_e32 v76, v209, v76, vcc
	v_cndmask_b32_e32 v75, v209, v75, vcc
	v_cndmask_b32_e32 v74, v209, v74, vcc
	v_cndmask_b32_e32 v73, v209, v73, vcc
	v_cndmask_b32_e32 v72, v209, v72, vcc
	v_cndmask_b32_e32 v71, v209, v71, vcc
	v_cndmask_b32_e32 v70, v209, v70, vcc
	v_cndmask_b32_e32 v69, v209, v69, vcc
	v_cndmask_b32_e32 v68, v209, v68, vcc
	v_cndmask_b32_e32 v67, v209, v67, vcc
	v_cndmask_b32_e32 v66, v209, v66, vcc
	global_store_dwordx4 v[148:149], v[90:93], off nt
	global_store_dwordx4 v[148:149], v[74:77], off offset:64 nt
	global_store_dwordx4 v[148:149], v[70:73], off offset:512 nt
	global_store_dwordx4 v[148:149], v[66:69], off offset:576 nt
	ds_read_b32 v66, v195
	s_mov_b64 s[8:9], -1
	v_add_u32_e32 v68, s62, v223
	v_ashrrev_i32_e32 v69, 31, v68
	v_lshlrev_b64 v[68:69], 14, v[68:69]
	s_waitcnt lgkmcnt(0)
	v_pk_mul_f32 v[36:37], v[36:37], v[66:67] op_sel_hi:[1,0]
	v_pk_mul_f32 v[34:35], v[34:35], v[66:67] op_sel_hi:[1,0]
	v_pk_mul_f32 v[36:37], v[16:17], v[36:37]
	v_pk_mul_f32 v[34:35], v[14:15], v[34:35]
	v_lshl_add_u64 v[68:69], v[164:165], 0, v[68:69]
	v_cndmask_b32_e32 v37, v209, v37, vcc
	v_cndmask_b32_e32 v36, v209, v36, vcc
	v_cndmask_b32_e32 v35, v209, v35, vcc
	v_cndmask_b32_e32 v34, v209, v34, vcc
	v_pk_mul_f32 v[48:49], v[48:49], v[66:67] op_sel_hi:[1,0]
	v_pk_mul_f32 v[46:47], v[46:47], v[66:67] op_sel_hi:[1,0]
	v_pk_mul_f32 v[44:45], v[44:45], v[66:67] op_sel_hi:[1,0]
	v_pk_mul_f32 v[42:43], v[42:43], v[66:67] op_sel_hi:[1,0]
	global_store_dwordx4 v[68:69], v[34:37], off offset:512 nt
	v_pk_mul_f32 v[48:49], v[140:141], v[48:49]
	v_pk_mul_f32 v[46:47], v[138:139], v[46:47]
	v_pk_mul_f32 v[34:35], v[40:41], v[66:67] op_sel_hi:[1,0]
	v_pk_mul_f32 v[36:37], v[38:39], v[66:67] op_sel_hi:[1,0]
	v_pk_mul_f32 v[44:45], v[132:133], v[44:45]
	v_pk_mul_f32 v[42:43], v[130:131], v[42:43]
	v_pk_mul_f32 v[34:35], v[8:9], v[34:35]
	v_pk_mul_f32 v[38:39], v[6:7], v[36:37]
	v_cndmask_b32_e32 v49, v209, v49, vcc
	v_cndmask_b32_e32 v48, v209, v48, vcc
	v_cndmask_b32_e32 v47, v209, v47, vcc
	v_cndmask_b32_e32 v46, v209, v46, vcc
	v_cndmask_b32_e32 v45, v209, v45, vcc
	v_cndmask_b32_e32 v44, v209, v44, vcc
	v_cndmask_b32_e32 v43, v209, v43, vcc
	v_cndmask_b32_e32 v42, v209, v42, vcc
	v_cndmask_b32_e32 v37, v209, v35, vcc
	v_cndmask_b32_e32 v36, v209, v34, vcc
	v_cndmask_b32_e32 v35, v209, v39, vcc
	v_cndmask_b32_e32 v34, v209, v38, vcc
	global_store_dwordx4 v[68:69], v[46:49], off nt
	global_store_dwordx4 v[68:69], v[42:45], off offset:64 nt
	global_store_dwordx4 v[68:69], v[34:37], off offset:576 nt
	ds_read_b32 v38, v196
	s_nop 0
	v_add_u32_e32 v34, s62, v254
	v_ashrrev_i32_e32 v35, 31, v34
	v_lshlrev_b64 v[40:41], 14, v[34:35]
	s_waitcnt lgkmcnt(0)
	v_pk_mul_f32 v[34:35], v[128:129], v[38:39] op_sel_hi:[1,0]
	v_pk_mul_f32 v[36:37], v[126:127], v[38:39] op_sel_hi:[1,0]
	v_pk_mul_f32 v[34:35], v[140:141], v[34:35]
	v_pk_mul_f32 v[42:43], v[138:139], v[36:37]
	v_cndmask_b32_e32 v37, v209, v35, vcc
	v_cndmask_b32_e32 v36, v209, v34, vcc
	v_cndmask_b32_e32 v35, v209, v43, vcc
	v_cndmask_b32_e32 v34, v209, v42, vcc
	v_lshl_add_u64 v[40:41], v[164:165], 0, v[40:41]
	global_store_dwordx4 v[40:41], v[34:37], off nt
	s_nop 1
	v_pk_mul_f32 v[34:35], v[124:125], v[38:39] op_sel_hi:[1,0]
	v_pk_mul_f32 v[36:37], v[122:123], v[38:39] op_sel_hi:[1,0]
	v_pk_mul_f32 v[34:35], v[132:133], v[34:35]
	v_pk_mul_f32 v[42:43], v[130:131], v[36:37]
	v_cndmask_b32_e32 v37, v209, v35, vcc
	v_cndmask_b32_e32 v36, v209, v34, vcc
	v_cndmask_b32_e32 v35, v209, v43, vcc
	v_cndmask_b32_e32 v34, v209, v42, vcc
	global_store_dwordx4 v[40:41], v[34:37], off offset:64 nt
	s_nop 1
	v_pk_mul_f32 v[34:35], v[120:121], v[38:39] op_sel_hi:[1,0]
	v_pk_mul_f32 v[36:37], v[118:119], v[38:39] op_sel_hi:[1,0]
	v_pk_mul_f32 v[34:35], v[16:17], v[34:35]
	v_pk_mul_f32 v[42:43], v[14:15], v[36:37]
	v_cndmask_b32_e32 v37, v209, v35, vcc
	v_cndmask_b32_e32 v36, v209, v34, vcc
	v_cndmask_b32_e32 v35, v209, v43, vcc
	v_cndmask_b32_e32 v34, v209, v42, vcc
	global_store_dwordx4 v[40:41], v[34:37], off offset:512 nt
	s_nop 1
	v_pk_mul_f32 v[34:35], v[116:117], v[38:39] op_sel_hi:[1,0]
	v_pk_mul_f32 v[36:37], v[114:115], v[38:39] op_sel_hi:[1,0]
	v_pk_mul_f32 v[34:35], v[8:9], v[34:35]
	v_pk_mul_f32 v[38:39], v[6:7], v[36:37]
	v_cndmask_b32_e32 v37, v209, v35, vcc
	v_cndmask_b32_e32 v36, v209, v34, vcc
	v_cndmask_b32_e32 v35, v209, v39, vcc
	v_cndmask_b32_e32 v34, v209, v38, vcc
	global_store_dwordx4 v[40:41], v[34:37], off offset:576 nt
	ds_read_b32 v38, v197
	s_nop 0
	v_add_u32_e32 v34, s62, v190
	v_ashrrev_i32_e32 v35, 31, v34
	v_lshlrev_b64 v[40:41], 14, v[34:35]
	s_waitcnt lgkmcnt(0)
	v_pk_mul_f32 v[34:35], v[112:113], v[38:39] op_sel_hi:[1,0]
	v_pk_mul_f32 v[36:37], v[110:111], v[38:39] op_sel_hi:[1,0]
	v_pk_mul_f32 v[34:35], v[140:141], v[34:35]
	v_pk_mul_f32 v[42:43], v[138:139], v[36:37]
	v_cndmask_b32_e32 v37, v209, v35, vcc
	v_cndmask_b32_e32 v36, v209, v34, vcc
	v_cndmask_b32_e32 v35, v209, v43, vcc
	v_cndmask_b32_e32 v34, v209, v42, vcc
	v_lshl_add_u64 v[40:41], v[164:165], 0, v[40:41]
	global_store_dwordx4 v[40:41], v[34:37], off nt
	s_nop 1
	v_pk_mul_f32 v[34:35], v[108:109], v[38:39] op_sel_hi:[1,0]
	v_pk_mul_f32 v[36:37], v[106:107], v[38:39] op_sel_hi:[1,0]
	v_pk_mul_f32 v[34:35], v[132:133], v[34:35]
	v_pk_mul_f32 v[42:43], v[130:131], v[36:37]
	v_cndmask_b32_e32 v37, v209, v35, vcc
	v_cndmask_b32_e32 v36, v209, v34, vcc
	v_cndmask_b32_e32 v35, v209, v43, vcc
	v_cndmask_b32_e32 v34, v209, v42, vcc
	global_store_dwordx4 v[40:41], v[34:37], off offset:64 nt
	s_nop 1
	v_pk_mul_f32 v[34:35], v[104:105], v[38:39] op_sel_hi:[1,0]
	v_pk_mul_f32 v[36:37], v[102:103], v[38:39] op_sel_hi:[1,0]
	v_pk_mul_f32 v[34:35], v[16:17], v[34:35]
	v_pk_mul_f32 v[42:43], v[14:15], v[36:37]
	v_cndmask_b32_e32 v37, v209, v35, vcc
	v_cndmask_b32_e32 v36, v209, v34, vcc
	v_cndmask_b32_e32 v35, v209, v43, vcc
	v_cndmask_b32_e32 v34, v209, v42, vcc
	global_store_dwordx4 v[40:41], v[34:37], off offset:512 nt
	s_nop 1
	v_pk_mul_f32 v[34:35], v[100:101], v[38:39] op_sel_hi:[1,0]
	v_pk_mul_f32 v[36:37], v[98:99], v[38:39] op_sel_hi:[1,0]
	v_pk_mul_f32 v[34:35], v[8:9], v[34:35]
	v_pk_mul_f32 v[38:39], v[6:7], v[36:37]
	v_cndmask_b32_e32 v37, v209, v35, vcc
	v_cndmask_b32_e32 v36, v209, v34, vcc
	v_cndmask_b32_e32 v35, v209, v39, vcc
	v_cndmask_b32_e32 v34, v209, v38, vcc
	global_store_dwordx4 v[40:41], v[34:37], off offset:576 nt
	ds_read_b32 v38, v198
	v_lshlrev_b64 v[40:41], 14, v[174:175]
	v_lshl_add_u64 v[40:41], v[164:165], 0, v[40:41]
	s_waitcnt lgkmcnt(0)
	v_pk_mul_f32 v[34:35], v[96:97], v[38:39] op_sel_hi:[1,0]
	v_pk_mul_f32 v[36:37], v[94:95], v[38:39] op_sel_hi:[1,0]
	v_pk_mul_f32 v[34:35], v[140:141], v[34:35]
	v_pk_mul_f32 v[42:43], v[138:139], v[36:37]
	v_cndmask_b32_e32 v37, v209, v35, vcc
	v_cndmask_b32_e32 v36, v209, v34, vcc
	v_cndmask_b32_e32 v35, v209, v43, vcc
	v_cndmask_b32_e32 v34, v209, v42, vcc
	global_store_dwordx4 v[40:41], v[34:37], off nt
	s_nop 1
	v_pk_mul_f32 v[34:35], v[88:89], v[38:39] op_sel_hi:[1,0]
	v_pk_mul_f32 v[36:37], v[86:87], v[38:39] op_sel_hi:[1,0]
	v_pk_mul_f32 v[34:35], v[132:133], v[34:35]
	v_pk_mul_f32 v[42:43], v[130:131], v[36:37]
	v_cndmask_b32_e32 v37, v209, v35, vcc
	v_cndmask_b32_e32 v36, v209, v34, vcc
	v_cndmask_b32_e32 v35, v209, v43, vcc
	v_cndmask_b32_e32 v34, v209, v42, vcc
	global_store_dwordx4 v[40:41], v[34:37], off offset:64 nt
	s_nop 1
	v_pk_mul_f32 v[34:35], v[64:65], v[38:39] op_sel_hi:[1,0]
	v_pk_mul_f32 v[36:37], v[62:63], v[38:39] op_sel_hi:[1,0]
	v_pk_mul_f32 v[34:35], v[16:17], v[34:35]
	v_pk_mul_f32 v[42:43], v[14:15], v[36:37]
	v_cndmask_b32_e32 v37, v209, v35, vcc
	v_cndmask_b32_e32 v36, v209, v34, vcc
	v_cndmask_b32_e32 v35, v209, v43, vcc
	v_cndmask_b32_e32 v34, v209, v42, vcc
	global_store_dwordx4 v[40:41], v[34:37], off offset:512 nt
	s_nop 1
	v_pk_mul_f32 v[34:35], v[60:61], v[38:39] op_sel_hi:[1,0]
	v_pk_mul_f32 v[36:37], v[58:59], v[38:39] op_sel_hi:[1,0]
	v_pk_mul_f32 v[34:35], v[8:9], v[34:35]
	v_pk_mul_f32 v[38:39], v[6:7], v[36:37]
	v_cndmask_b32_e32 v37, v209, v35, vcc
	v_cndmask_b32_e32 v36, v209, v34, vcc
	v_cndmask_b32_e32 v35, v209, v39, vcc
	v_cndmask_b32_e32 v34, v209, v38, vcc
	global_store_dwordx4 v[40:41], v[34:37], off offset:576 nt
	ds_read_b32 v38, v199
	s_nop 0
	v_add_u32_e32 v34, s62, v191
	v_ashrrev_i32_e32 v35, 31, v34
	v_lshlrev_b64 v[40:41], 14, v[34:35]
	s_waitcnt lgkmcnt(0)
	v_pk_mul_f32 v[34:35], v[84:85], v[38:39] op_sel_hi:[1,0]
	v_pk_mul_f32 v[36:37], v[82:83], v[38:39] op_sel_hi:[1,0]
	v_pk_mul_f32 v[34:35], v[140:141], v[34:35]
	v_pk_mul_f32 v[42:43], v[138:139], v[36:37]
	v_cndmask_b32_e32 v37, v209, v35, vcc
	v_cndmask_b32_e32 v36, v209, v34, vcc
	v_cndmask_b32_e32 v35, v209, v43, vcc
	v_cndmask_b32_e32 v34, v209, v42, vcc
	v_lshl_add_u64 v[40:41], v[164:165], 0, v[40:41]
	global_store_dwordx4 v[40:41], v[34:37], off nt
	s_nop 1
	v_pk_mul_f32 v[34:35], v[80:81], v[38:39] op_sel_hi:[1,0]
	v_pk_mul_f32 v[36:37], v[78:79], v[38:39] op_sel_hi:[1,0]
	v_pk_mul_f32 v[34:35], v[132:133], v[34:35]
	v_pk_mul_f32 v[42:43], v[130:131], v[36:37]
	v_cndmask_b32_e32 v37, v209, v35, vcc
	v_cndmask_b32_e32 v36, v209, v34, vcc
	v_cndmask_b32_e32 v35, v209, v43, vcc
	v_cndmask_b32_e32 v34, v209, v42, vcc
	global_store_dwordx4 v[40:41], v[34:37], off offset:64 nt
	s_nop 1
	v_pk_mul_f32 v[34:35], v[56:57], v[38:39] op_sel_hi:[1,0]
	v_pk_mul_f32 v[36:37], v[54:55], v[38:39] op_sel_hi:[1,0]
	v_pk_mul_f32 v[34:35], v[16:17], v[34:35]
	v_pk_mul_f32 v[42:43], v[14:15], v[36:37]
	v_cndmask_b32_e32 v37, v209, v35, vcc
	v_cndmask_b32_e32 v36, v209, v34, vcc
	v_cndmask_b32_e32 v35, v209, v43, vcc
	v_cndmask_b32_e32 v34, v209, v42, vcc
	global_store_dwordx4 v[40:41], v[34:37], off offset:512 nt
	s_nop 1
	v_pk_mul_f32 v[34:35], v[52:53], v[38:39] op_sel_hi:[1,0]
	v_pk_mul_f32 v[36:37], v[50:51], v[38:39] op_sel_hi:[1,0]
	v_pk_mul_f32 v[34:35], v[8:9], v[34:35]
	v_pk_mul_f32 v[38:39], v[6:7], v[36:37]
	v_cndmask_b32_e32 v37, v209, v35, vcc
	v_cndmask_b32_e32 v36, v209, v34, vcc
	v_cndmask_b32_e32 v35, v209, v39, vcc
	v_cndmask_b32_e32 v34, v209, v38, vcc
	global_store_dwordx4 v[40:41], v[34:37], off offset:576 nt
	ds_read_b32 v38, v200
	s_waitcnt lgkmcnt(0)
	v_pk_mul_f32 v[32:33], v[32:33], v[38:39] op_sel_hi:[1,0]
	v_add_u32_e32 v34, s62, v192
	v_ashrrev_i32_e32 v35, 31, v34
	v_lshlrev_b64 v[40:41], 14, v[34:35]
	v_pk_mul_f32 v[34:35], v[144:145], v[38:39] op_sel_hi:[1,0]
	v_pk_mul_f32 v[36:37], v[142:143], v[38:39] op_sel_hi:[1,0]
	v_pk_mul_f32 v[34:35], v[140:141], v[34:35]
	v_pk_mul_f32 v[42:43], v[138:139], v[36:37]
	v_cndmask_b32_e32 v37, v209, v35, vcc
	v_cndmask_b32_e32 v36, v209, v34, vcc
	v_cndmask_b32_e32 v35, v209, v43, vcc
	v_cndmask_b32_e32 v34, v209, v42, vcc
	v_lshl_add_u64 v[40:41], v[164:165], 0, v[40:41]
	global_store_dwordx4 v[40:41], v[34:37], off nt
	v_pk_mul_f32 v[30:31], v[30:31], v[38:39] op_sel_hi:[1,0]
	v_pk_mul_f32 v[28:29], v[28:29], v[38:39] op_sel_hi:[1,0]
	v_pk_mul_f32 v[34:35], v[136:137], v[38:39] op_sel_hi:[1,0]
	v_pk_mul_f32 v[36:37], v[134:135], v[38:39] op_sel_hi:[1,0]
	v_pk_mul_f32 v[26:27], v[26:27], v[38:39] op_sel_hi:[1,0]
	v_pk_mul_f32 v[34:35], v[132:133], v[34:35]
	v_pk_mul_f32 v[42:43], v[130:131], v[36:37]
	v_pk_mul_f32 v[32:33], v[16:17], v[32:33]
	v_pk_mul_f32 v[30:31], v[14:15], v[30:31]
	v_pk_mul_f32 v[28:29], v[8:9], v[28:29]
	v_pk_mul_f32 v[26:27], v[6:7], v[26:27]
	v_cndmask_b32_e32 v37, v209, v35, vcc
	v_cndmask_b32_e32 v36, v209, v34, vcc
	v_cndmask_b32_e32 v35, v209, v43, vcc
	v_cndmask_b32_e32 v34, v209, v42, vcc
	v_cndmask_b32_e32 v33, v209, v33, vcc
	v_cndmask_b32_e32 v32, v209, v32, vcc
	v_cndmask_b32_e32 v31, v209, v31, vcc
	v_cndmask_b32_e32 v30, v209, v30, vcc
	v_cndmask_b32_e32 v29, v209, v29, vcc
	v_cndmask_b32_e32 v28, v209, v28, vcc
	v_cndmask_b32_e32 v27, v209, v27, vcc
	v_cndmask_b32_e32 v26, v209, v26, vcc
	global_store_dwordx4 v[40:41], v[34:37], off offset:64 nt
	global_store_dwordx4 v[40:41], v[30:33], off offset:512 nt
	global_store_dwordx4 v[40:41], v[26:29], off offset:576 nt
	ds_read_b32 v26, v201
	s_waitcnt lgkmcnt(0)
	v_pk_mul_f32 v[24:25], v[24:25], v[26:27] op_sel_hi:[1,0]
	v_add_u32_e32 v28, s62, v193
	v_ashrrev_i32_e32 v29, 31, v28
	v_pk_mul_f32 v[22:23], v[22:23], v[26:27] op_sel_hi:[1,0]
	v_pk_mul_f32 v[20:21], v[20:21], v[26:27] op_sel_hi:[1,0]
	v_pk_mul_f32 v[18:19], v[18:19], v[26:27] op_sel_hi:[1,0]
	v_pk_mul_f32 v[12:13], v[12:13], v[26:27] op_sel_hi:[1,0]
	v_pk_mul_f32 v[10:11], v[10:11], v[26:27] op_sel_hi:[1,0]
	v_pk_mul_f32 v[4:5], v[4:5], v[26:27] op_sel_hi:[1,0]
	v_pk_mul_f32 v[2:3], v[2:3], v[26:27] op_sel_hi:[1,0]
	v_lshlrev_b64 v[28:29], 14, v[28:29]
	v_pk_mul_f32 v[24:25], v[140:141], v[24:25]
	v_pk_mul_f32 v[22:23], v[138:139], v[22:23]
	v_pk_mul_f32 v[20:21], v[132:133], v[20:21]
	v_pk_mul_f32 v[18:19], v[130:131], v[18:19]
	v_pk_mul_f32 v[12:13], v[16:17], v[12:13]
	v_pk_mul_f32 v[10:11], v[14:15], v[10:11]
	v_pk_mul_f32 v[4:5], v[8:9], v[4:5]
	v_pk_mul_f32 v[2:3], v[6:7], v[2:3]
	v_cndmask_b32_e32 v25, v209, v25, vcc
	v_cndmask_b32_e32 v24, v209, v24, vcc
	v_cndmask_b32_e32 v23, v209, v23, vcc
	v_cndmask_b32_e32 v22, v209, v22, vcc
	v_lshl_add_u64 v[28:29], v[164:165], 0, v[28:29]
	v_cndmask_b32_e32 v21, v209, v21, vcc
	v_cndmask_b32_e32 v20, v209, v20, vcc
	v_cndmask_b32_e32 v19, v209, v19, vcc
	v_cndmask_b32_e32 v18, v209, v18, vcc
	v_cndmask_b32_e32 v13, v209, v13, vcc
	v_cndmask_b32_e32 v12, v209, v12, vcc
	v_cndmask_b32_e32 v11, v209, v11, vcc
	v_cndmask_b32_e32 v10, v209, v10, vcc
	v_cndmask_b32_e32 v5, v209, v5, vcc
	v_cndmask_b32_e32 v4, v209, v4, vcc
	v_cndmask_b32_e32 v3, v209, v3, vcc
	v_cndmask_b32_e32 v2, v209, v2, vcc
	global_store_dwordx4 v[28:29], v[22:25], off nt
	global_store_dwordx4 v[28:29], v[18:21], off offset:64 nt
	global_store_dwordx4 v[28:29], v[10:13], off offset:512 nt
	global_store_dwordx4 v[28:29], v[2:5], off offset:576 nt
	s_andn2_b64 vcc, exec, s[38:39]
	s_cbranch_vccnz .LBB0_1038
	s_andn2_b64 vcc, exec, s[28:29]
	s_cbranch_vccnz .LBB0_1037
	s_barrier
	s_branch .LBB0_1037
